# a_w_out transposes also moved out of phase 0 into the A-in tail (phase 0 now converts only a_w_in: exactly two items per wave)
# baseline (speedup 1.0000x reference)
.Lp0_skipzero:
	v_ashrrev_i32_e32 v8, 6, v2
	s_lshl_b32 s0, s2, 3
	v_and_b32_e32 v47, 63, v2
	v_writelane_b32 v255, s0, 0
	v_add_u32_e32 v51, s0, v8
	s_movk_i32 s0, 0x3800
	s_lshl_b32 s33, s52, 3
	s_cmp_eq_u32 s98, 0
	s_cselect_b32 s0, 0x1000, s71
	s_cselect_b32 s33, s33, s72
	s_cselect_b32 s60, 0, s70
	v_add_u32_e32 v51, s60, v51
	v_cmp_gt_i32_e32 vcc, s0, v51
	v_lshlrev_b32_e32 v18, 3, v47
	s_and_saveexec_b64 s[28:29], vcc
	s_cbranch_execz .LBB0_34
	v_lshrrev_b32_e32 v19, 5, v47
	v_and_b32_e32 v26, 31, v2
	s_movk_i32 s0, 0x84
	v_mov_b32_e32 v2, 0x630
	v_mad_u32_u24 v35, v19, s0, v2
	v_mov_b32_e32 v2, 0xc60
	v_mad_u32_u24 v42, v19, s0, v2
	v_mov_b32_e32 v2, 0x1290
	v_mad_u32_u24 v53, v19, s0, v2
	v_mov_b32_e32 v2, 0x18c0
	v_mad_u32_u24 v60, v19, s0, v2
	v_and_b32_e32 v2, 56, v18
	v_lshrrev_b32_e32 v68, 3, v47
	v_mul_u32_u24_e32 v9, 0x84, v2
	v_lshlrev_b32_e32 v2, 1, v2
	v_mov_b32_e32 v3, 0
	v_lshl_add_u32 v7, v8, 14, 0
	s_waitcnt lgkmcnt(0)
	v_lshl_add_u64 v[4:5], s[22:23], 0, v[2:3]
	v_lshlrev_b32_e32 v2, 2, v68
	v_add3_u32 v69, v7, v9, v2
	v_lshlrev_b32_e32 v2, 5, v8
	v_lshl_add_u32 v74, s2, 8, v2
	v_lshlrev_b32_e32 v2, 7, v8
	v_lshlrev_b32_e32 v6, 2, v26
	v_lshl_add_u32 v75, s2, 10, v2
	v_lshlrev_b32_e32 v2, 6, v8
	v_add_u32_e32 v27, v7, v6
	v_mov_b32_e32 v7, v3
	v_lshl_add_u32 v76, s2, 9, v2
	v_lshlrev_b32_e32 v2, 1, v8
	s_mov_b64 s[36:37], 0x3600000
	s_mov_b64 s[38:39], 0x2d00000
	s_mov_b64 s[40:41], 0x2500000
	s_mov_b64 s[42:43], 0x1c00000
	s_mov_b64 s[44:45], 0x1400000
	s_mov_b64 s[46:47], 0x1000000
	v_lshl_add_u64 v[6:7], s[30:31], 0, v[6:7]
	s_add_u32 s30, s24, 0x1000
	v_lshl_add_u32 v2, s2, 4, v2
	v_mul_u32_u24_e32 v28, 0x84, v19
	v_or_b32_e32 v29, 2, v19
	v_or_b32_e32 v30, 4, v19
	v_or_b32_e32 v31, 6, v19
	v_or_b32_e32 v32, 8, v19
	v_or_b32_e32 v33, 10, v19
	v_or_b32_e32 v34, 12, v19
	v_or_b32_e32 v36, 14, v19
	v_or_b32_e32 v37, 16, v19
	v_or_b32_e32 v38, 18, v19
	v_or_b32_e32 v39, 20, v19
	v_or_b32_e32 v40, 22, v19
	v_or_b32_e32 v41, 24, v19
	v_or_b32_e32 v43, 26, v19
	v_or_b32_e32 v46, 28, v19
	v_or_b32_e32 v48, 30, v19
	v_or_b32_e32 v49, 32, v19
	v_or_b32_e32 v50, 34, v19
	v_or_b32_e32 v52, 36, v19
	v_or_b32_e32 v54, 38, v19
	v_or_b32_e32 v55, 40, v19
	v_or_b32_e32 v56, 42, v19
	v_or_b32_e32 v57, 44, v19
	v_or_b32_e32 v58, 46, v19
	v_or_b32_e32 v59, 48, v19
	v_or_b32_e32 v61, 50, v19
	v_or_b32_e32 v62, 52, v19
	v_or_b32_e32 v63, 54, v19
	v_or_b32_e32 v64, 56, v19
	v_or_b32_e32 v65, 58, v19
	v_or_b32_e32 v66, 60, v19
	v_or_b32_e32 v67, 62, v19
	v_or_b32_e32 v70, 8, v68
	v_or_b32_e32 v71, 16, v68
	v_or_b32_e32 v72, 24, v68
	v_bitop3_b32 v73, v68, 15, 24 bitop3:0xc8
	s_addc_u32 s31, s25, 0
	s_lshl_b32 s0, s33, 5
	s_lshl_b32 s1, s33, 7
	s_lshl_b32 s3, s33, 6
	v_add_u32_e32 v77, 0x19800, v2
	s_lshl_b32 s48, s33, 1
	s_mov_b64 s[34:35], 0
	s_movk_i32 s49, 0xfff
	s_movk_i32 s50, 0x13ff
	s_movk_i32 s51, 0x1bff
	s_movk_i32 s53, 0x23ff
	s_movk_i32 s54, 0x2bff
	s_movk_i32 s55, 0x33ff
	s_movk_i32 s56, 0x7fff
	s_mov_b32 s57, 0xffff0000
	s_movk_i32 s58, 0x37ff
	v_mov_b32_e32 v78, v51
	v_lshl_add_u64 v[8:9], v[4:5], 0, s[36:37]
	v_lshl_add_u64 v[10:11], v[4:5], 0, s[38:39]
	v_lshl_add_u64 v[12:13], v[4:5], 0, s[40:41]
	v_lshl_add_u64 v[14:15], v[4:5], 0, s[42:43]
	v_lshl_add_u64 v[16:17], v[4:5], 0, s[44:45]
	v_lshl_add_u64 v[20:21], v[4:5], 0, s[46:47]
	s_cmp_eq_u32 s98, 0
	s_cselect_b32 s58, 0xfff, s75
	s_cselect_b32 s60, 0, s76
	s_cselect_b32 s61, 0, s77
	v_add_u32_e32 v74, s60, v74
	v_add_u32_e32 v75, s61, v75
	s_cselect_b32 s60, 0, s78
	s_cselect_b32 s61, 0, s79
	v_add_u32_e32 v76, s60, v76
	v_add_u32_e32 v77, s61, v77
	s_branch .LBB0_10

.LBB0_232:
	s_cmp_lt_u32 s2, 0x80
	s_cbranch_scc1 .Lp1_resume
	s_mov_b32 s98, 3
	s_mov_b32 s70, 0xc00
	s_mov_b32 s71, 0x2c00
	s_mov_b32 s72, 0x400
	s_mov_b32 s73, 0x0
	s_mov_b32 s74, 0x0
	s_mov_b32 s75, 0x2bff
	s_lshl_b32 s76, s70, 5
	s_lshl_b32 s77, s70, 7
	s_lshl_b32 s78, s70, 6
	s_lshl_b32 s79, s70, 1
	s_branch .Lp0_entry
